# remaining cross-block rsqrt(x+eps) sequences simplified (8 sites)
# baseline (speedup 1.0000x reference)
; __device__ __forceinline__ unsigned pk_bf16(float lo, float hi) { f32x2 v = {lo, hi}; bf16x2_t b = __builtin_convertvector(v, bf16x2_t); return __builtin_bit_cast(unsigned, b); }
;     __device__ __forceinline__ void operator()(const f32x4 (&acc)[2][2][4][2], const Unit& u, int wr, int wc, int fr, int fq) const {
;     ...
;                         const int row = row0 + ai * HALF + m * 16;
;                         const float rv = rsqrtf(rowss[row] * (1.0f / 1024.0f) + 1e-6f);
;                         const f32x4 v0 = (acc[ai][bj][m][0] * rv + bz0) * qsc, v1 = (acc[ai][bj][m][1] * rv + bz1) * qsc;
;                         if (isk) { float s2 = (v0[0] * v0[0] + v0[1] * v0[1]) + (v0[2] * v0[2] + v0[3] * v0[3]) + (v1[0] * v1[0] + v1[1] * v1[1]) + (v1[2] * v1[2] + v1[3] * v1[3]);
;                             s2 += __shfl_xor(s2, 16); s2 += __shfl_xor(s2, 32); kmx = fmaxf(kmx, s2); }
;                         u32x4 w; w.x = pk_bf16(v0[0], v0[1]); w.y = pk_bf16(v0[2], v0[3]); w.z = pk_bf16(v1[0], v1[1]); w.w = pk_bf16(v1[2], v1[3]);
;                         *(u32x4*)(base + (size_t)row * pitch) = w;
.LBB0_313:
	v_rsq_f32_e32 v73, v72
	s_or_b64 vcc, s[74:75], s[4:5]
	v_cndmask_b32_e32 v72, 1.0, v231, vcc
	s_andn2_b64 vcc, exec, s[6:7]
	v_mov_b32_e32 v74, v73
	v_pk_fma_f32 v[78:79], v[60:61], v[74:75], v[68:69] op_sel_hi:[1,0,1]
	v_pk_fma_f32 v[60:61], v[62:63], v[74:75], v[70:71] op_sel_hi:[1,0,1]
	v_pk_fma_f32 v[56:57], v[56:57], v[74:75], v[64:65] op_sel_hi:[1,0,1]
	v_pk_fma_f32 v[58:59], v[58:59], v[74:75], v[66:67] op_sel_hi:[1,0,1]
	v_pk_mul_f32 v[60:61], v[72:73], v[60:61] op_sel_hi:[0,1]
	v_pk_mul_f32 v[62:63], v[72:73], v[78:79] op_sel_hi:[0,1]
	v_pk_mul_f32 v[58:59], v[72:73], v[58:59] op_sel_hi:[0,1]
	v_pk_mul_f32 v[74:75], v[72:73], v[56:57] op_sel_hi:[0,1]
	v_mov_b32_e32 v77, 0
	s_cbranch_vccnz .LBB0_315
	v_pk_mul_f32 v[56:57], v[60:61], v[60:61]
	v_pk_mul_f32 v[78:79], v[62:63], v[62:63]
	v_and_b32_e32 v73, 64, v230
	v_pk_mov_b32 v[82:83], v[78:79], v[56:57] op_sel:[1,0]
	v_mov_b32_e32 v79, v57
	v_pk_add_f32 v[56:57], v[82:83], v[78:79]
	v_pk_mul_f32 v[78:79], v[58:59], v[58:59]
	v_pk_mul_f32 v[82:83], v[74:75], v[74:75]
	v_mov_b32_e32 v84, v78
	v_mov_b32_e32 v85, v82
	v_mov_b32_e32 v82, v79
	v_add_f32_e32 v56, v56, v57
	v_xor_b32_e32 v57, 16, v230
	v_add_u32_e32 v73, 64, v73
	v_pk_add_f32 v[78:79], v[84:85], v[82:83]
	v_cmp_lt_i32_e32 vcc, v57, v73
	v_add_f32_e32 v56, v79, v56
	v_add_f32_e32 v56, v78, v56
	v_cndmask_b32_e32 v57, v230, v57, vcc
	v_lshlrev_b32_e32 v57, 2, v57
	ds_bpermute_b32 v57, v57, v56
	s_waitcnt lgkmcnt(0)
	v_add_f32_e32 v56, v56, v57
	v_xor_b32_e32 v57, 32, v230
	v_cmp_lt_i32_e32 vcc, v57, v73
	s_nop 1
	v_cndmask_b32_e32 v57, v230, v57, vcc
	v_lshlrev_b32_e32 v57, 2, v57
	ds_bpermute_b32 v57, v57, v56
	s_waitcnt lgkmcnt(0)
	v_add_f32_e32 v56, v56, v57
	v_max_f32_e32 v77, 0, v56

; __device__ __forceinline__ unsigned pk_bf16(float lo, float hi) { f32x2 v = {lo, hi}; bf16x2_t b = __builtin_convertvector(v, bf16x2_t); return __builtin_bit_cast(unsigned, b); }
;     __device__ __forceinline__ void operator()(const f32x4 (&acc)[2][2][4][2], const Unit& u, int wr, int wc, int fr, int fq) const {
;     ...
;                         const int row = row0 + ai * HALF + m * 16;
;                         const float rv = rsqrtf(rowss[row] * (1.0f / 1024.0f) + 1e-6f);
;                         const f32x4 v0 = (acc[ai][bj][m][0] * rv + bz0) * qsc, v1 = (acc[ai][bj][m][1] * rv + bz1) * qsc;
;                         if (isk) { float s2 = (v0[0] * v0[0] + v0[1] * v0[1]) + (v0[2] * v0[2] + v0[3] * v0[3]) + (v1[0] * v1[0] + v1[1] * v1[1]) + (v1[2] * v1[2] + v1[3] * v1[3]);
;                             s2 += __shfl_xor(s2, 16); s2 += __shfl_xor(s2, 32); kmx = fmaxf(kmx, s2); }
;                         u32x4 w; w.x = pk_bf16(v0[0], v0[1]); w.y = pk_bf16(v0[2], v0[3]); w.z = pk_bf16(v1[0], v1[1]); w.w = pk_bf16(v1[2], v1[3]);
;                         *(u32x4*)(base + (size_t)row * pitch) = w;
.LBB0_319:
	v_rsq_f32_e32 v60, v58
	v_mov_b32_e32 v58, v72
	v_mov_b32_e32 v59, v72
	s_andn2_b64 vcc, exec, s[4:5]
	v_pk_fma_f32 v[62:63], v[52:53], v[60:61], v[68:69] op_sel_hi:[1,0,1]
	v_pk_fma_f32 v[52:53], v[54:55], v[60:61], v[70:71] op_sel_hi:[1,0,1]
	v_pk_mul_f32 v[54:55], v[72:73], v[62:63]
	v_pk_fma_f32 v[62:63], v[48:49], v[60:61], v[64:65] op_sel_hi:[1,0,1]
	v_pk_fma_f32 v[48:49], v[50:51], v[60:61], v[66:67] op_sel_hi:[1,0,1]
	v_pk_mul_f32 v[52:53], v[58:59], v[52:53]
	v_pk_mul_f32 v[48:49], v[58:59], v[48:49]
	v_pk_mul_f32 v[50:51], v[72:73], v[62:63]
	s_cbranch_vccnz .LBB0_321
	v_pk_mul_f32 v[58:59], v[52:53], v[52:53]
	v_pk_mul_f32 v[60:61], v[54:55], v[54:55]
	s_nop 0
	v_pk_mov_b32 v[62:63], v[60:61], v[58:59] op_sel:[1,0]
	v_mov_b32_e32 v61, v59
	v_pk_add_f32 v[58:59], v[62:63], v[60:61]
	v_pk_mul_f32 v[60:61], v[48:49], v[48:49]
	v_pk_mul_f32 v[62:63], v[50:51], v[50:51]
	v_mov_b32_e32 v74, v60
	v_mov_b32_e32 v75, v62
	v_mov_b32_e32 v62, v61
	v_pk_add_f32 v[60:61], v[74:75], v[62:63]
	v_add_f32_e32 v58, v58, v59
	v_add_f32_e32 v58, v61, v58
	v_add_f32_e32 v58, v60, v58
	v_and_b32_e32 v60, 64, v230
	v_xor_b32_e32 v59, 16, v230
	v_add_u32_e32 v60, 64, v60
	v_cmp_lt_i32_e32 vcc, v59, v60
	s_nop 1
	v_cndmask_b32_e32 v59, v230, v59, vcc
	v_lshlrev_b32_e32 v59, 2, v59
	ds_bpermute_b32 v59, v59, v58
	s_waitcnt lgkmcnt(0)
	v_add_f32_e32 v58, v58, v59
	v_xor_b32_e32 v59, 32, v230
	v_cmp_lt_i32_e32 vcc, v59, v60
	s_nop 1
	v_cndmask_b32_e32 v59, v230, v59, vcc
	v_lshlrev_b32_e32 v59, 2, v59
	ds_bpermute_b32 v59, v59, v58
	s_waitcnt lgkmcnt(0)
	v_add_f32_e32 v58, v58, v59
	v_max_f32_e32 v59, v77, v77
	v_max_f32_e32 v77, v59, v58

; __device__ __forceinline__ unsigned pk_bf16(float lo, float hi) { f32x2 v = {lo, hi}; bf16x2_t b = __builtin_convertvector(v, bf16x2_t); return __builtin_bit_cast(unsigned, b); }
;     __device__ __forceinline__ void operator()(const f32x4 (&acc)[2][2][4][2], const Unit& u, int wr, int wc, int fr, int fq) const {
;     ...
;                         const int row = row0 + ai * HALF + m * 16;
;                         const float rv = rsqrtf(rowss[row] * (1.0f / 1024.0f) + 1e-6f);
;                         const f32x4 v0 = (acc[ai][bj][m][0] * rv + bz0) * qsc, v1 = (acc[ai][bj][m][1] * rv + bz1) * qsc;
;                         if (isk) { float s2 = (v0[0] * v0[0] + v0[1] * v0[1]) + (v0[2] * v0[2] + v0[3] * v0[3]) + (v1[0] * v1[0] + v1[1] * v1[1]) + (v1[2] * v1[2] + v1[3] * v1[3]);
;                             s2 += __shfl_xor(s2, 16); s2 += __shfl_xor(s2, 32); kmx = fmaxf(kmx, s2); }
;                         u32x4 w; w.x = pk_bf16(v0[0], v0[1]); w.y = pk_bf16(v0[2], v0[3]); w.z = pk_bf16(v1[0], v1[1]); w.w = pk_bf16(v1[2], v1[3]);
;                         *(u32x4*)(base + (size_t)row * pitch) = w;
.LBB0_325:
	v_rsq_f32_e32 v50, v48
	v_mov_b32_e32 v48, v72
	v_mov_b32_e32 v49, v72
	s_andn2_b64 vcc, exec, s[4:5]
	v_pk_fma_f32 v[52:53], v[44:45], v[50:51], v[68:69] op_sel_hi:[1,0,1]
	v_pk_fma_f32 v[44:45], v[46:47], v[50:51], v[70:71] op_sel_hi:[1,0,1]
	v_pk_mul_f32 v[46:47], v[72:73], v[52:53]
	v_pk_fma_f32 v[52:53], v[40:41], v[50:51], v[64:65] op_sel_hi:[1,0,1]
	v_pk_fma_f32 v[40:41], v[42:43], v[50:51], v[66:67] op_sel_hi:[1,0,1]
	v_pk_mul_f32 v[44:45], v[48:49], v[44:45]
	v_pk_mul_f32 v[40:41], v[48:49], v[40:41]
	v_pk_mul_f32 v[42:43], v[72:73], v[52:53]
	s_cbranch_vccnz .LBB0_327
	v_pk_mul_f32 v[48:49], v[44:45], v[44:45]
	v_pk_mul_f32 v[50:51], v[46:47], v[46:47]
	s_nop 0
	v_pk_mov_b32 v[52:53], v[50:51], v[48:49] op_sel:[1,0]
	v_mov_b32_e32 v51, v49
	v_pk_add_f32 v[48:49], v[52:53], v[50:51]
	v_pk_mul_f32 v[50:51], v[40:41], v[40:41]
	v_pk_mul_f32 v[52:53], v[42:43], v[42:43]
	v_mov_b32_e32 v54, v50
	v_mov_b32_e32 v55, v52
	v_mov_b32_e32 v52, v51
	v_pk_add_f32 v[50:51], v[54:55], v[52:53]
	v_add_f32_e32 v48, v48, v49
	v_add_f32_e32 v48, v51, v48
	v_add_f32_e32 v48, v50, v48
	v_and_b32_e32 v50, 64, v230
	v_xor_b32_e32 v49, 16, v230
	v_add_u32_e32 v50, 64, v50
	v_cmp_lt_i32_e32 vcc, v49, v50
	s_nop 1
	v_cndmask_b32_e32 v49, v230, v49, vcc
	v_lshlrev_b32_e32 v49, 2, v49
	ds_bpermute_b32 v49, v49, v48
	s_waitcnt lgkmcnt(0)
	v_add_f32_e32 v48, v48, v49
	v_xor_b32_e32 v49, 32, v230
	v_cmp_lt_i32_e32 vcc, v49, v50
	s_nop 1
	v_cndmask_b32_e32 v49, v230, v49, vcc
	v_lshlrev_b32_e32 v49, 2, v49
	ds_bpermute_b32 v49, v49, v48
	s_waitcnt lgkmcnt(0)
	v_add_f32_e32 v48, v48, v49
	v_max_f32_e32 v49, v77, v77
	v_max_f32_e32 v77, v49, v48

; __device__ __forceinline__ unsigned pk_bf16(float lo, float hi) { f32x2 v = {lo, hi}; bf16x2_t b = __builtin_convertvector(v, bf16x2_t); return __builtin_bit_cast(unsigned, b); }
;     __device__ __forceinline__ void operator()(const f32x4 (&acc)[2][2][4][2], const Unit& u, int wr, int wc, int fr, int fq) const {
;     ...
;                         const int row = row0 + ai * HALF + m * 16;
;                         const float rv = rsqrtf(rowss[row] * (1.0f / 1024.0f) + 1e-6f);
;                         const f32x4 v0 = (acc[ai][bj][m][0] * rv + bz0) * qsc, v1 = (acc[ai][bj][m][1] * rv + bz1) * qsc;
;                         if (isk) { float s2 = (v0[0] * v0[0] + v0[1] * v0[1]) + (v0[2] * v0[2] + v0[3] * v0[3]) + (v1[0] * v1[0] + v1[1] * v1[1]) + (v1[2] * v1[2] + v1[3] * v1[3]);
;                             s2 += __shfl_xor(s2, 16); s2 += __shfl_xor(s2, 32); kmx = fmaxf(kmx, s2); }
;                         u32x4 w; w.x = pk_bf16(v0[0], v0[1]); w.y = pk_bf16(v0[2], v0[3]); w.z = pk_bf16(v1[0], v1[1]); w.w = pk_bf16(v1[2], v1[3]);
;                         *(u32x4*)(base + (size_t)row * pitch) = w;
.LBB0_331:
	v_rsq_f32_e32 v42, v40
	v_mov_b32_e32 v40, v72
	v_mov_b32_e32 v41, v72
	s_andn2_b64 vcc, exec, s[4:5]
	v_pk_fma_f32 v[44:45], v[36:37], v[42:43], v[68:69] op_sel_hi:[1,0,1]
	v_pk_fma_f32 v[36:37], v[38:39], v[42:43], v[70:71] op_sel_hi:[1,0,1]
	v_pk_mul_f32 v[38:39], v[72:73], v[44:45]
	v_pk_fma_f32 v[44:45], v[32:33], v[42:43], v[64:65] op_sel_hi:[1,0,1]
	v_pk_fma_f32 v[32:33], v[34:35], v[42:43], v[66:67] op_sel_hi:[1,0,1]
	v_pk_mul_f32 v[36:37], v[40:41], v[36:37]
	v_pk_mul_f32 v[32:33], v[40:41], v[32:33]
	v_pk_mul_f32 v[34:35], v[72:73], v[44:45]
	s_cbranch_vccnz .LBB0_333
	v_pk_mul_f32 v[40:41], v[36:37], v[36:37]
	v_pk_mul_f32 v[42:43], v[38:39], v[38:39]
	s_nop 0
	v_pk_mov_b32 v[44:45], v[42:43], v[40:41] op_sel:[1,0]
	v_mov_b32_e32 v43, v41
	v_pk_add_f32 v[40:41], v[44:45], v[42:43]
	v_pk_mul_f32 v[42:43], v[32:33], v[32:33]
	v_pk_mul_f32 v[44:45], v[34:35], v[34:35]
	v_mov_b32_e32 v46, v42
	v_mov_b32_e32 v47, v44
	v_mov_b32_e32 v44, v43
	v_pk_add_f32 v[42:43], v[46:47], v[44:45]
	v_add_f32_e32 v40, v40, v41
	v_add_f32_e32 v40, v43, v40
	v_add_f32_e32 v40, v42, v40
	v_and_b32_e32 v42, 64, v230
	v_xor_b32_e32 v41, 16, v230
	v_add_u32_e32 v42, 64, v42
	v_cmp_lt_i32_e32 vcc, v41, v42
	s_nop 1
	v_cndmask_b32_e32 v41, v230, v41, vcc
	v_lshlrev_b32_e32 v41, 2, v41
	ds_bpermute_b32 v41, v41, v40
	s_waitcnt lgkmcnt(0)
	v_add_f32_e32 v40, v40, v41
	v_xor_b32_e32 v41, 32, v230
	v_cmp_lt_i32_e32 vcc, v41, v42
	s_nop 1
	v_cndmask_b32_e32 v41, v230, v41, vcc
	v_lshlrev_b32_e32 v41, 2, v41
	ds_bpermute_b32 v41, v41, v40
	s_waitcnt lgkmcnt(0)
	v_add_f32_e32 v40, v40, v41
	v_max_f32_e32 v41, v77, v77
	v_max_f32_e32 v77, v41, v40

; __device__ __forceinline__ unsigned pk_bf16(float lo, float hi) { f32x2 v = {lo, hi}; bf16x2_t b = __builtin_convertvector(v, bf16x2_t); return __builtin_bit_cast(unsigned, b); }
;     __device__ __forceinline__ void operator()(const f32x4 (&acc)[2][2][4][2], const Unit& u, int wr, int wc, int fr, int fq) const {
;     ...
;                         const int row = row0 + ai * HALF + m * 16;
;                         const float rv = rsqrtf(rowss[row] * (1.0f / 1024.0f) + 1e-6f);
;                         const f32x4 v0 = (acc[ai][bj][m][0] * rv + bz0) * qsc, v1 = (acc[ai][bj][m][1] * rv + bz1) * qsc;
;                         if (isk) { float s2 = (v0[0] * v0[0] + v0[1] * v0[1]) + (v0[2] * v0[2] + v0[3] * v0[3]) + (v1[0] * v1[0] + v1[1] * v1[1]) + (v1[2] * v1[2] + v1[3] * v1[3]);
;                             s2 += __shfl_xor(s2, 16); s2 += __shfl_xor(s2, 32); kmx = fmaxf(kmx, s2); }
;                         u32x4 w; w.x = pk_bf16(v0[0], v0[1]); w.y = pk_bf16(v0[2], v0[3]); w.z = pk_bf16(v1[0], v1[1]); w.w = pk_bf16(v1[2], v1[3]);
;                         *(u32x4*)(base + (size_t)row * pitch) = w;
.LBB0_337:
	v_rsq_f32_e32 v34, v32
	v_mov_b32_e32 v32, v72
	v_mov_b32_e32 v33, v72
	s_andn2_b64 vcc, exec, s[4:5]
	v_pk_fma_f32 v[36:37], v[28:29], v[34:35], v[68:69] op_sel_hi:[1,0,1]
	v_pk_fma_f32 v[28:29], v[30:31], v[34:35], v[70:71] op_sel_hi:[1,0,1]
	v_pk_mul_f32 v[30:31], v[72:73], v[36:37]
	v_pk_fma_f32 v[36:37], v[24:25], v[34:35], v[64:65] op_sel_hi:[1,0,1]
	v_pk_fma_f32 v[24:25], v[26:27], v[34:35], v[66:67] op_sel_hi:[1,0,1]
	v_pk_mul_f32 v[28:29], v[32:33], v[28:29]
	v_pk_mul_f32 v[24:25], v[32:33], v[24:25]
	v_pk_mul_f32 v[26:27], v[72:73], v[36:37]
	s_cbranch_vccnz .LBB0_339
	v_pk_mul_f32 v[32:33], v[28:29], v[28:29]
	v_pk_mul_f32 v[34:35], v[30:31], v[30:31]
	s_nop 0
	v_pk_mov_b32 v[36:37], v[34:35], v[32:33] op_sel:[1,0]
	v_mov_b32_e32 v35, v33
	v_pk_add_f32 v[32:33], v[36:37], v[34:35]
	v_pk_mul_f32 v[34:35], v[24:25], v[24:25]
	v_pk_mul_f32 v[36:37], v[26:27], v[26:27]
	v_mov_b32_e32 v38, v34
	v_mov_b32_e32 v39, v36
	v_mov_b32_e32 v36, v35
	v_pk_add_f32 v[34:35], v[38:39], v[36:37]
	v_add_f32_e32 v32, v32, v33
	v_add_f32_e32 v32, v35, v32
	v_add_f32_e32 v32, v34, v32
	v_and_b32_e32 v34, 64, v230
	v_xor_b32_e32 v33, 16, v230
	v_add_u32_e32 v34, 64, v34
	v_cmp_lt_i32_e32 vcc, v33, v34
	s_nop 1
	v_cndmask_b32_e32 v33, v230, v33, vcc
	v_lshlrev_b32_e32 v33, 2, v33
	ds_bpermute_b32 v33, v33, v32
	s_waitcnt lgkmcnt(0)
	v_add_f32_e32 v32, v32, v33
	v_xor_b32_e32 v33, 32, v230
	v_cmp_lt_i32_e32 vcc, v33, v34
	s_nop 1
	v_cndmask_b32_e32 v33, v230, v33, vcc
	v_lshlrev_b32_e32 v33, 2, v33
	ds_bpermute_b32 v33, v33, v32
	s_waitcnt lgkmcnt(0)
	v_add_f32_e32 v32, v32, v33
	v_max_f32_e32 v33, v77, v77
	v_max_f32_e32 v77, v33, v32

;     __device__ __forceinline__ void operator()(const f32x4 (&acc)[2][2][4][2], const Unit& u, int wr, int wc, int fr, int fq) const {
;     ...
;                     for (int m = 0; m < 4; ++m) {
;                         const int row = row0 + ai * HALF + m * 16;
;                         const float rv = rsqrtf(rowss[row] * (1.0f / 1024.0f) + 1e-6f);
;                         const f32x4 v0 = (acc[ai][bj][m][0] * rv + bz0) * qsc, v1 = (acc[ai][bj][m][1] * rv + bz1) * qsc;
;                         if (isk) { float s2 = (v0[0] * v0[0] + v0[1] * v0[1]) + (v0[2] * v0[2] + v0[3] * v0[3]) + (v1[0] * v1[0] + v1[1] * v1[1]) + (v1[2] * v1[2] + v1[3] * v1[3]);
;                             s2 += __shfl_xor(s2, 16); s2 += __shfl_xor(s2, 32); kmx = fmaxf(kmx, s2); }
.LBB0_343:
	v_rsq_f32_e32 v26, v24
	v_mov_b32_e32 v24, v72
	v_mov_b32_e32 v25, v72
	s_andn2_b64 vcc, exec, s[4:5]
	v_pk_fma_f32 v[28:29], v[20:21], v[26:27], v[68:69] op_sel_hi:[1,0,1]
	v_pk_fma_f32 v[20:21], v[22:23], v[26:27], v[70:71] op_sel_hi:[1,0,1]
	v_pk_mul_f32 v[22:23], v[72:73], v[28:29]
	v_pk_fma_f32 v[28:29], v[16:17], v[26:27], v[64:65] op_sel_hi:[1,0,1]
	v_pk_fma_f32 v[16:17], v[18:19], v[26:27], v[66:67] op_sel_hi:[1,0,1]
	v_pk_mul_f32 v[20:21], v[24:25], v[20:21]
	v_pk_mul_f32 v[16:17], v[24:25], v[16:17]
	v_pk_mul_f32 v[18:19], v[72:73], v[28:29]
	s_cbranch_vccnz .LBB0_345
	v_pk_mul_f32 v[24:25], v[20:21], v[20:21]
	v_pk_mul_f32 v[26:27], v[22:23], v[22:23]
	s_nop 0
	v_pk_mov_b32 v[28:29], v[26:27], v[24:25] op_sel:[1,0]
	v_mov_b32_e32 v27, v25
	v_pk_add_f32 v[24:25], v[28:29], v[26:27]
	v_pk_mul_f32 v[26:27], v[16:17], v[16:17]
	v_pk_mul_f32 v[28:29], v[18:19], v[18:19]
	v_mov_b32_e32 v30, v26
	v_mov_b32_e32 v31, v28
	v_mov_b32_e32 v28, v27
	v_pk_add_f32 v[26:27], v[30:31], v[28:29]
	v_add_f32_e32 v24, v24, v25
	v_add_f32_e32 v24, v27, v24
	v_add_f32_e32 v24, v26, v24
	v_and_b32_e32 v26, 64, v230
	v_xor_b32_e32 v25, 16, v230
	v_add_u32_e32 v26, 64, v26
	v_cmp_lt_i32_e32 vcc, v25, v26
	s_nop 1
	v_cndmask_b32_e32 v25, v230, v25, vcc
	v_lshlrev_b32_e32 v25, 2, v25
	ds_bpermute_b32 v25, v25, v24
	s_waitcnt lgkmcnt(0)
	v_add_f32_e32 v24, v24, v25
	v_xor_b32_e32 v25, 32, v230
	v_cmp_lt_i32_e32 vcc, v25, v26
	s_nop 1
	v_cndmask_b32_e32 v25, v230, v25, vcc
	v_lshlrev_b32_e32 v25, 2, v25
	ds_bpermute_b32 v25, v25, v24
	s_waitcnt lgkmcnt(0)
	v_add_f32_e32 v24, v24, v25
	v_max_f32_e32 v25, v77, v77
	v_max_f32_e32 v77, v25, v24

;     __device__ __forceinline__ void operator()(const f32x4 (&acc)[2][2][4][2], const Unit& u, int wr, int wc, int fr, int fq) const {
;     ...
;                     for (int m = 0; m < 4; ++m) {
;                         const int row = row0 + ai * HALF + m * 16;
;                         const float rv = rsqrtf(rowss[row] * (1.0f / 1024.0f) + 1e-6f);
;                         const f32x4 v0 = (acc[ai][bj][m][0] * rv + bz0) * qsc, v1 = (acc[ai][bj][m][1] * rv + bz1) * qsc;
;                         if (isk) { float s2 = (v0[0] * v0[0] + v0[1] * v0[1]) + (v0[2] * v0[2] + v0[3] * v0[3]) + (v1[0] * v1[0] + v1[1] * v1[1]) + (v1[2] * v1[2] + v1[3] * v1[3]);
;                             s2 += __shfl_xor(s2, 16); s2 += __shfl_xor(s2, 32); kmx = fmaxf(kmx, s2); }
.LBB0_349:
	v_rsq_f32_e32 v18, v16
	v_mov_b32_e32 v16, v72
	v_mov_b32_e32 v17, v72
	s_andn2_b64 vcc, exec, s[4:5]
	v_pk_fma_f32 v[20:21], v[12:13], v[18:19], v[68:69] op_sel_hi:[1,0,1]
	v_pk_fma_f32 v[12:13], v[14:15], v[18:19], v[70:71] op_sel_hi:[1,0,1]
	v_pk_mul_f32 v[14:15], v[72:73], v[20:21]
	v_pk_fma_f32 v[20:21], v[8:9], v[18:19], v[64:65] op_sel_hi:[1,0,1]
	v_pk_fma_f32 v[8:9], v[10:11], v[18:19], v[66:67] op_sel_hi:[1,0,1]
	v_pk_mul_f32 v[12:13], v[16:17], v[12:13]
	v_pk_mul_f32 v[8:9], v[16:17], v[8:9]
	v_pk_mul_f32 v[10:11], v[72:73], v[20:21]
	s_cbranch_vccnz .LBB0_351
	v_pk_mul_f32 v[16:17], v[12:13], v[12:13]
	v_pk_mul_f32 v[18:19], v[14:15], v[14:15]
	s_nop 0
	v_pk_mov_b32 v[20:21], v[18:19], v[16:17] op_sel:[1,0]
	v_mov_b32_e32 v19, v17
	v_pk_add_f32 v[16:17], v[20:21], v[18:19]
	v_pk_mul_f32 v[18:19], v[8:9], v[8:9]
	v_pk_mul_f32 v[20:21], v[10:11], v[10:11]
	v_mov_b32_e32 v22, v18
	v_mov_b32_e32 v23, v20
	v_mov_b32_e32 v20, v19
	v_pk_add_f32 v[18:19], v[22:23], v[20:21]
	v_add_f32_e32 v16, v16, v17
	v_add_f32_e32 v16, v19, v16
	v_add_f32_e32 v16, v18, v16
	v_and_b32_e32 v18, 64, v230
	v_xor_b32_e32 v17, 16, v230
	v_add_u32_e32 v18, 64, v18
	v_cmp_lt_i32_e32 vcc, v17, v18
	s_nop 1
	v_cndmask_b32_e32 v17, v230, v17, vcc
	v_lshlrev_b32_e32 v17, 2, v17
	ds_bpermute_b32 v17, v17, v16
	s_waitcnt lgkmcnt(0)
	v_add_f32_e32 v16, v16, v17
	v_xor_b32_e32 v17, 32, v230
	v_cmp_lt_i32_e32 vcc, v17, v18
	s_nop 1
	v_cndmask_b32_e32 v17, v230, v17, vcc
	v_lshlrev_b32_e32 v17, 2, v17
	ds_bpermute_b32 v17, v17, v16
	s_waitcnt lgkmcnt(0)
	v_add_f32_e32 v16, v16, v17
	v_max_f32_e32 v17, v77, v77
	v_max_f32_e32 v77, v17, v16

;     __device__ __forceinline__ void operator()(const f32x4 (&acc)[2][2][4][2], const Unit& u, int wr, int wc, int fr, int fq) const {
;     ...
;                     for (int m = 0; m < 4; ++m) {
;                         const int row = row0 + ai * HALF + m * 16;
;                         const float rv = rsqrtf(rowss[row] * (1.0f / 1024.0f) + 1e-6f);
;                         const f32x4 v0 = (acc[ai][bj][m][0] * rv + bz0) * qsc, v1 = (acc[ai][bj][m][1] * rv + bz1) * qsc;
;                         if (isk) { float s2 = (v0[0] * v0[0] + v0[1] * v0[1]) + (v0[2] * v0[2] + v0[3] * v0[3]) + (v1[0] * v1[0] + v1[1] * v1[1]) + (v1[2] * v1[2] + v1[3] * v1[3]);
;                             s2 += __shfl_xor(s2, 16); s2 += __shfl_xor(s2, 32); kmx = fmaxf(kmx, s2); }
.LBB0_355:
	v_rsq_f32_e32 v8, v8
	v_mov_b32_e32 v12, v72
	v_mov_b32_e32 v13, v72
	s_andn2_b64 vcc, exec, s[4:5]
	v_pk_fma_f32 v[10:11], v[4:5], v[8:9], v[68:69] op_sel_hi:[1,0,1]
	v_pk_fma_f32 v[4:5], v[6:7], v[8:9], v[70:71] op_sel_hi:[1,0,1]
	v_pk_mul_f32 v[6:7], v[72:73], v[10:11]
	v_pk_fma_f32 v[10:11], v[0:1], v[8:9], v[64:65] op_sel_hi:[1,0,1]
	v_pk_fma_f32 v[0:1], v[2:3], v[8:9], v[66:67] op_sel_hi:[1,0,1]
	v_pk_mul_f32 v[4:5], v[12:13], v[4:5]
	v_pk_mul_f32 v[0:1], v[12:13], v[0:1]
	v_pk_mul_f32 v[2:3], v[72:73], v[10:11]
	s_cbranch_vccnz .LBB0_357
	v_pk_mul_f32 v[8:9], v[4:5], v[4:5]
	v_pk_mul_f32 v[10:11], v[6:7], v[6:7]
	s_nop 0
	v_pk_mov_b32 v[12:13], v[10:11], v[8:9] op_sel:[1,0]
	v_mov_b32_e32 v11, v9
	v_pk_add_f32 v[8:9], v[12:13], v[10:11]
	v_pk_mul_f32 v[10:11], v[0:1], v[0:1]
	v_pk_mul_f32 v[12:13], v[2:3], v[2:3]
	v_mov_b32_e32 v14, v10
	v_mov_b32_e32 v15, v12
	v_mov_b32_e32 v12, v11
	v_pk_add_f32 v[10:11], v[14:15], v[12:13]
	v_add_f32_e32 v8, v8, v9
	v_add_f32_e32 v8, v11, v8
	v_add_f32_e32 v8, v10, v8
	v_and_b32_e32 v10, 64, v230
	v_xor_b32_e32 v9, 16, v230
	v_add_u32_e32 v10, 64, v10
	v_cmp_lt_i32_e32 vcc, v9, v10
	s_nop 1
	v_cndmask_b32_e32 v9, v230, v9, vcc
	v_lshlrev_b32_e32 v9, 2, v9
	ds_bpermute_b32 v9, v9, v8
	s_waitcnt lgkmcnt(0)
	v_add_f32_e32 v8, v8, v9
	v_xor_b32_e32 v9, 32, v230
	v_cmp_lt_i32_e32 vcc, v9, v10
	s_nop 1
	v_cndmask_b32_e32 v9, v230, v9, vcc
	v_lshlrev_b32_e32 v9, 2, v9
	ds_bpermute_b32 v9, v9, v8
	s_waitcnt lgkmcnt(0)
	v_add_f32_e32 v8, v8, v9
	v_max_f32_e32 v9, v77, v77
	v_max_f32_e32 v77, v9, v8
